# MLA step head: K/V load addresses by one 64-bit add against a scalar constant pair instead of v_add_co / s_nop / v_addc_co triples
# baseline (speedup 1.0000x reference)
; #define LOADT(RK, RV, tt) do { const char* kb_ = (const char*)(Kb + (size_t)(tt) * (64 * 192)); const char* vb_ = (const char*)(Vb + (size_t)(tt) * 64); \
;     _Pragma("unroll") for (int i = 0; i < 3; ++i) RK[i] = *(const u32x4*)(kb_ + i * 8192 + kgo); \
;     _Pragma("unroll") for (int i = 0; i < 2; ++i) RV[i] = *(const u32x4*)(vb_ + (size_t)i * (64 * S * 2) + vgo); } while (0)
; #define STORET(RK, RV, kbuf, vbuf) do { \
;     _Pragma("unroll") for (int i = 0; i < 3; ++i) *(LAS u32x4*)(L + (kbuf) * (2 * MLA_KS) + kds[i]) = RK[i]; \
;     _Pragma("unroll") for (int i = 0; i < 2; ++i) { LAS u32x2* d_ = (LAS u32x2*)(L + (vbuf) * (2 * MLA_VS) + vds + i * (64 * 36)); d_[0] = (u32x2){RV[i].x, RV[i].y}; d_[1] = (u32x2){RV[i].z, RV[i].w}; } } while (0)
; __device__ __forceinline__ void mla_unit(LAS unsigned char* lds, int bh, int x, const bf16* QM, const bf16* KM, const bf16* VMT, bf16* OUT, ssq_t* SSo, int tid, int lane, int wave) {
;     ...
;         __syncthreads();
;         if (t + 1 < T) STORET(rk0, rv0, 0, (vb == 2) ? 0 : vb + 1);
;         if (t + 3 < T) LOADT(rk0, rv0, t + 3);
.LBB0_1296:
	s_mul_i32 s16, s18, 0x2400
	s_add_i32 s14, s16, 0x2400
	s_cmp_eq_u32 s18, 2
	s_cselect_b64 s[10:11], -1, 0
	s_and_b64 s[8:9], s[10:11], exec
	s_cselect_b32 s8, 0, s14
	s_add_i32 s49, s4, 2
	s_cmp_ge_u32 s49, s45
	v_lshl_add_u32 v82, s8, 1, v214
	s_cselect_b64 s[8:9], -1, 0
	v_add_u32_e32 v83, 0xc800, v82
	v_add_u32_e32 v82, 0xda00, v82
	s_and_b64 vcc, exec, s[8:9]
	v_lshl_add_u64 v[192:193], v[188:189], 0, s[2:3]
	v_lshl_add_u64 v[190:191], v[186:187], 0, s[2:3]
	s_barrier
	s_waitcnt vmcnt(4)
	ds_write_b128 v211, v[124:127]
	s_waitcnt vmcnt(3)
	ds_write_b128 v212, v[128:131]
	s_waitcnt vmcnt(2)
	ds_write_b128 v213, v[132:135]
	s_waitcnt vmcnt(1)
	ds_write2_b64 v83, v[136:137], v[138:139] offset1:1
	s_waitcnt vmcnt(0)
	ds_write2_b64 v82, v[144:145], v[146:147] offset1:1
	s_cbranch_vccnz .LBB0_1298
	s_mov_b32 s90, 0x9d18000
	s_mov_b32 s91, 0
	v_lshl_add_u64 v[82:83], v[192:193], 0, s[90:91]
	s_mov_b32 s90, 0x9d1a000
	s_mov_b32 s91, 0
	v_lshl_add_u64 v[84:85], v[192:193], 0, s[90:91]
	global_load_dwordx4 v[124:127], v[82:83], off
	global_load_dwordx4 v[128:131], v[84:85], off
	s_mov_b32 s90, 0x9d1c000
	s_mov_b32 s91, 0
	v_lshl_add_u64 v[82:83], v[192:193], 0, s[90:91]
	global_load_dwordx4 v[132:135], v[82:83], off
	s_mov_b32 s90, 0xb500000
	s_mov_b32 s91, 0
	v_lshl_add_u64 v[82:83], v[190:191], 0, s[90:91]
	s_mov_b32 s90, 0xb600000
	s_mov_b32 s91, 0
	v_lshl_add_u64 v[84:85], v[190:191], 0, s[90:91]
	global_load_dwordx4 v[136:139], v[82:83], off offset:512
	global_load_dwordx4 v[144:147], v[84:85], off offset:512

; #define LOADT(RK, RV, tt) do { const char* kb_ = (const char*)(Kb + (size_t)(tt) * (64 * 192)); const char* vb_ = (const char*)(Vb + (size_t)(tt) * 64); \
;     _Pragma("unroll") for (int i = 0; i < 3; ++i) RK[i] = *(const u32x4*)(kb_ + i * 8192 + kgo); \
;     _Pragma("unroll") for (int i = 0; i < 2; ++i) RV[i] = *(const u32x4*)(vb_ + (size_t)i * (64 * S * 2) + vgo); } while (0)
; #define STORET(RK, RV, kbuf, vbuf) do { \
;     _Pragma("unroll") for (int i = 0; i < 3; ++i) *(LAS u32x4*)(L + (kbuf) * (2 * MLA_KS) + kds[i]) = RK[i]; \
;     _Pragma("unroll") for (int i = 0; i < 2; ++i) { LAS u32x2* d_ = (LAS u32x2*)(L + (vbuf) * (2 * MLA_VS) + vds + i * (64 * 36)); d_[0] = (u32x2){RV[i].x, RV[i].y}; d_[1] = (u32x2){RV[i].z, RV[i].w}; } } while (0)
; __device__ __forceinline__ void mla_unit(LAS unsigned char* lds, int bh, int x, const bf16* QM, const bf16* KM, const bf16* VMT, bf16* OUT, ssq_t* SSo, int tid, int lane, int wave) {
;     ...
;         if (t + 2 < T) STORET(rk1, rv1, 1, (vb == 2) ? 0 : vb + 1);
;         if (t + 4 < T) LOADT(rk1, rv1, t + 4);
.LBB0_1304:
	s_add_i32 s14, s4, 3
	s_cmp_ge_u32 s14, s45
	s_cbranch_scc1 .LBB0_1306
	s_mov_b32 s90, 0x9d1e000
	s_mov_b32 s91, 0
	v_lshl_add_u64 v[66:67], v[192:193], 0, s[90:91]
	s_mov_b32 s90, 0x9d20000
	s_mov_b32 s91, 0
	v_lshl_add_u64 v[68:69], v[192:193], 0, s[90:91]
	global_load_dwordx4 v[140:143], v[66:67], off
	global_load_dwordx4 v[148:151], v[68:69], off
	s_mov_b32 s90, 0x9d22000
	s_mov_b32 s91, 0
	v_lshl_add_u64 v[66:67], v[192:193], 0, s[90:91]
	global_load_dwordx4 v[152:155], v[66:67], off
	s_mov_b32 s90, 0xb500000
	s_mov_b32 s91, 0
	v_lshl_add_u64 v[66:67], v[190:191], 0, s[90:91]
	s_mov_b32 s90, 0xb600000
	s_mov_b32 s91, 0
	v_lshl_add_u64 v[68:69], v[190:191], 0, s[90:91]
	global_load_dwordx4 v[156:159], v[66:67], off offset:640
	global_load_dwordx4 v[160:163], v[68:69], off offset:640
